# grid barrier: leaders and non-leaders wait on the arrival counter itself (>= (k+1)*#XCDs) instead of a generation word bumped after the last arrival returned
# speedup vs baseline: 1.0137x; 1.0001x over previous
; DI unsigned xb_ld(unsigned* p)              { return __hip_atomic_load(p, __ATOMIC_RELAXED, __HIP_MEMORY_SCOPE_AGENT); }
; DI unsigned xb_add(unsigned* p, unsigned v) { return __hip_atomic_fetch_add(p, v, __ATOMIC_RELAXED, __HIP_MEMORY_SCOPE_AGENT); }
; #define XB_SPIN(cond, bar) do { unsigned _sp = 0; while (cond) { __builtin_amdgcn_s_sleep(1); \
;     if ((++_sp & 255u) == 0u) { if (xb_ld(&(bar)[XB_TMO])) break; if (_sp > XB_SPIN_CAP) { atomicAdd(&(bar)[XB_TMO], 1u); break; } } } } while (0)
; DI void xcd_barrier(const XcdBarrier& b) {
;     ...
;         const unsigned old = xb_add(&bar[XB_XSUB(b.x)], 1u);
;         const unsigned gen = old / nloc;
;         if (old + 1u == (gen + 1u) * nloc) {
;             __builtin_amdgcn_fence(__ATOMIC_RELEASE, "agent");
;             asm volatile("s_waitcnt vmcnt(0)" ::: "memory");
;             const unsigned og = xb_add(&bar[XB_TOP], 1u);
;             const unsigned tg = og / nx;
;             if (og + 1u == (tg + 1u) * nx) xb_add(&bar[XB_TOPGEN], 1u);
;             else XB_SPIN(xb_ld(&bar[XB_TOPGEN]) == tg, bar);
;             __builtin_amdgcn_fence(__ATOMIC_ACQUIRE, "agent");
;             xb_add(&bar[XB_XGEN(b.x)], 1u);
;             asm volatile("s_waitcnt vmcnt(0)" ::: "memory");
;         } else {
;             XB_SPIN(xb_ld(&bar[XB_XGEN(b.x)]) == gen, bar);
;             __builtin_amdgcn_fence(__ATOMIC_ACQUIRE, "agent");
;             asm volatile("s_waitcnt vmcnt(0)" ::: "memory");
;         }
.LBB0_124:
	s_or_b64 exec, exec, s[10:11]
	v_cvt_f32_u32_e32 v4, v2
	s_waitcnt vmcnt(0)
	v_readfirstlane_b32 s0, v3
	v_sub_u32_e32 v3, 0, v2
	v_rcp_iflag_f32_e32 v4, v4
	v_add_u32_e32 v5, s0, v1
	v_mul_f32_e32 v4, 0x4f7ffffe, v4
	v_cvt_u32_f32_e32 v4, v4
	v_mul_lo_u32 v1, v3, v4
	v_mul_hi_u32 v1, v4, v1
	v_add_u32_e32 v1, v4, v1
	v_mul_hi_u32 v1, v5, v1
	v_mul_lo_u32 v3, v1, v2
	v_sub_u32_e32 v3, v5, v3
	v_add_u32_e32 v4, 1, v1
	v_cmp_ge_u32_e32 vcc, v3, v2
	s_nop 1
	v_cndmask_b32_e32 v1, v1, v4, vcc
	v_sub_u32_e32 v4, v3, v2
	v_cndmask_b32_e32 v3, v3, v4, vcc
	v_add_u32_e32 v4, 1, v1
	v_cmp_ge_u32_e32 vcc, v3, v2
	v_add_u32_e32 v3, 1, v5
	s_nop 0
	v_cndmask_b32_e32 v1, v1, v4, vcc
	v_mul_lo_u32 v4, v2, v1
	v_add_u32_e32 v2, v4, v2
	v_cmp_ne_u32_e32 vcc, v3, v2
	s_and_saveexec_b64 s[0:1], vcc
	s_xor_b64 s[8:9], exec, s[0:1]
	s_cbranch_execz .LBB0_138
	s_waitcnt lgkmcnt(0)
	s_add_u32 s16, s70, 0xff20400
	s_addc_u32 s17, s71, 0
	v_mul_u32_u24_e32 v1, 1, v0
	v_mov_b32_e32 v0, 0
	global_load_dword v0, v0, s[16:17] sc1
	s_waitcnt vmcnt(0)
	v_cmp_lt_u32_e32 vcc, v0, v1
	s_and_saveexec_b64 s[10:11], vcc
	s_cbranch_execz .LBB0_137
	s_add_u32 s12, s70, 0xff1d200
	s_addc_u32 s13, s71, 0
	s_mov_b32 s0, 1
	s_mov_b64 s[18:19], 0
	v_mov_b32_e32 v0, 0
	s_branch .LBB0_128

; DI unsigned xb_ld(unsigned* p)              { return __hip_atomic_load(p, __ATOMIC_RELAXED, __HIP_MEMORY_SCOPE_AGENT); }
; #define XB_SPIN(cond, bar) do { unsigned _sp = 0; while (cond) { __builtin_amdgcn_s_sleep(1); \
;     if ((++_sp & 255u) == 0u) { if (xb_ld(&(bar)[XB_TMO])) break; if (_sp > XB_SPIN_CAP) { atomicAdd(&(bar)[XB_TMO], 1u); break; } } } } while (0)
; DI void xcd_barrier(const XcdBarrier& b) {
;     ...
;             XB_SPIN(xb_ld(&bar[XB_XGEN(b.x)]) == gen, bar);
.LBB0_130:
	global_load_dword v2, v0, s[16:17] sc1
	s_add_i32 s0, s0, 1
	s_mov_b64 s[24:25], -1
	s_waitcnt vmcnt(0)
	v_cmp_ge_u32_e32 vcc, v2, v1
	s_orn2_b64 s[22:23], vcc, exec
	s_branch .LBB0_127

; DI unsigned xb_ld(unsigned* p)              { return __hip_atomic_load(p, __ATOMIC_RELAXED, __HIP_MEMORY_SCOPE_AGENT); }
; DI unsigned xb_add(unsigned* p, unsigned v) { return __hip_atomic_fetch_add(p, v, __ATOMIC_RELAXED, __HIP_MEMORY_SCOPE_AGENT); }
; #define XB_SPIN(cond, bar) do { unsigned _sp = 0; while (cond) { __builtin_amdgcn_s_sleep(1); \
;     if ((++_sp & 255u) == 0u) { if (xb_ld(&(bar)[XB_TMO])) break; if (_sp > XB_SPIN_CAP) { atomicAdd(&(bar)[XB_TMO], 1u); break; } } } } while (0)
; DI void xcd_barrier(const XcdBarrier& b) {
;     ...
;             const unsigned og = xb_add(&bar[XB_TOP], 1u);
;             const unsigned tg = og / nx;
;             if (og + 1u == (tg + 1u) * nx) xb_add(&bar[XB_TOPGEN], 1u);
;             else XB_SPIN(xb_ld(&bar[XB_TOPGEN]) == tg, bar);
;             __builtin_amdgcn_fence(__ATOMIC_ACQUIRE, "agent");
.LBB0_141:
	s_or_b64 exec, exec, s[10:11]
	v_cvt_f32_u32_e32 v3, v0
	s_waitcnt vmcnt(0)
	v_readfirstlane_b32 s0, v2
	s_add_u32 s10, s70, 0xff20400
	s_addc_u32 s11, s71, 0
	v_rcp_iflag_f32_e32 v3, v3
	v_add_u32_e32 v1, s0, v1
	v_add_u32_e32 v4, 1, v1
	s_mov_b64 s[12:13], 0
	v_mul_f32_e32 v2, 0x4f7ffffe, v3
	v_cvt_u32_f32_e32 v2, v2
	v_sub_u32_e32 v3, 0, v0
	v_mul_lo_u32 v3, v3, v2
	v_mul_hi_u32 v3, v2, v3
	v_add_u32_e32 v2, v2, v3
	v_mul_hi_u32 v2, v1, v2
	v_mul_lo_u32 v3, v2, v0
	v_sub_u32_e32 v1, v1, v3
	v_add_u32_e32 v5, 1, v2
	v_cmp_ge_u32_e32 vcc, v1, v0
	v_sub_u32_e32 v3, v1, v0
	s_nop 0
	v_cndmask_b32_e32 v2, v2, v5, vcc
	v_cndmask_b32_e32 v1, v1, v3, vcc
	v_add_u32_e32 v3, 1, v2
	v_cmp_ge_u32_e32 vcc, v1, v0
	s_nop 1
	v_cndmask_b32_e32 v2, v2, v3, vcc
	v_mul_lo_u32 v1, v0, v2
	v_add_u32_e32 v0, v1, v0
	v_cmp_ne_u32_e32 vcc, v4, v0
	v_mov_b32_e32 v5, v0
	v_mov_b64_e32 v[0:1], s[10:11]
	s_and_saveexec_b64 s[8:9], vcc
	s_cbranch_execz .LBB0_153
	v_mov_b32_e32 v0, 0
	global_load_dword v1, v0, s[10:11] sc1
	s_mov_b64 s[18:19], 0
	s_waitcnt vmcnt(0)
	v_cmp_lt_u32_e32 vcc, v1, v5
	s_and_saveexec_b64 s[16:17], vcc
	s_cbranch_execz .LBB0_152
	s_add_u32 s12, s70, 0xff1d200
	s_addc_u32 s13, s71, 0
	s_mov_b32 s0, 1
	s_branch .LBB0_145

; DI unsigned xb_ld(unsigned* p)              { return __hip_atomic_load(p, __ATOMIC_RELAXED, __HIP_MEMORY_SCOPE_AGENT); }
; #define XB_SPIN(cond, bar) do { unsigned _sp = 0; while (cond) { __builtin_amdgcn_s_sleep(1); \
;     if ((++_sp & 255u) == 0u) { if (xb_ld(&(bar)[XB_TMO])) break; if (_sp > XB_SPIN_CAP) { atomicAdd(&(bar)[XB_TMO], 1u); break; } } } } while (0)
; DI void xcd_barrier(const XcdBarrier& b) {
;     ...
;             else XB_SPIN(xb_ld(&bar[XB_TOPGEN]) == tg, bar);
.LBB0_147:
	global_load_dword v1, v0, s[10:11] sc1
	s_add_i32 s0, s0, 1
	s_mov_b64 s[22:23], -1
	s_waitcnt vmcnt(0)
	v_cmp_ge_u32_e32 vcc, v1, v5
	s_orn2_b64 s[26:27], vcc, exec
	s_branch .LBB0_144

; DI unsigned xb_ld(unsigned* p)              { return __hip_atomic_load(p, __ATOMIC_RELAXED, __HIP_MEMORY_SCOPE_AGENT); }
; DI unsigned xb_add(unsigned* p, unsigned v) { return __hip_atomic_fetch_add(p, v, __ATOMIC_RELAXED, __HIP_MEMORY_SCOPE_AGENT); }
; #define XB_SPIN(cond, bar) do { unsigned _sp = 0; while (cond) { __builtin_amdgcn_s_sleep(1); \
;     if ((++_sp & 255u) == 0u) { if (xb_ld(&(bar)[XB_TMO])) break; if (_sp > XB_SPIN_CAP) { atomicAdd(&(bar)[XB_TMO], 1u); break; } } } } while (0)
; DI void xcd_barrier(const XcdBarrier& b) {
;     ...
;         const unsigned old = xb_add(&bar[XB_XSUB(b.x)], 1u);
;         const unsigned gen = old / nloc;
;         if (old + 1u == (gen + 1u) * nloc) {
;             __builtin_amdgcn_fence(__ATOMIC_RELEASE, "agent");
;             asm volatile("s_waitcnt vmcnt(0)" ::: "memory");
;             const unsigned og = xb_add(&bar[XB_TOP], 1u);
;             const unsigned tg = og / nx;
;             if (og + 1u == (tg + 1u) * nx) xb_add(&bar[XB_TOPGEN], 1u);
;             else XB_SPIN(xb_ld(&bar[XB_TOPGEN]) == tg, bar);
;             __builtin_amdgcn_fence(__ATOMIC_ACQUIRE, "agent");
;             xb_add(&bar[XB_XGEN(b.x)], 1u);
;             asm volatile("s_waitcnt vmcnt(0)" ::: "memory");
;         } else {
;             XB_SPIN(xb_ld(&bar[XB_XGEN(b.x)]) == gen, bar);
;             __builtin_amdgcn_fence(__ATOMIC_ACQUIRE, "agent");
;             asm volatile("s_waitcnt vmcnt(0)" ::: "memory");
;         }
.LBB0_1601:
	s_or_b64 exec, exec, s[10:11]
	v_cvt_f32_u32_e32 v4, v2
	s_waitcnt vmcnt(0)
	v_readfirstlane_b32 s0, v3
	v_sub_u32_e32 v3, 0, v2
	v_rcp_iflag_f32_e32 v4, v4
	v_add_u32_e32 v5, s0, v1
	v_mul_f32_e32 v4, 0x4f7ffffe, v4
	v_cvt_u32_f32_e32 v4, v4
	v_mul_lo_u32 v1, v3, v4
	v_mul_hi_u32 v1, v4, v1
	v_add_u32_e32 v1, v4, v1
	v_mul_hi_u32 v1, v5, v1
	v_mul_lo_u32 v3, v1, v2
	v_sub_u32_e32 v3, v5, v3
	v_add_u32_e32 v4, 1, v1
	v_cmp_ge_u32_e32 vcc, v3, v2
	s_nop 1
	v_cndmask_b32_e32 v1, v1, v4, vcc
	v_sub_u32_e32 v4, v3, v2
	v_cndmask_b32_e32 v3, v3, v4, vcc
	v_add_u32_e32 v4, 1, v1
	v_cmp_ge_u32_e32 vcc, v3, v2
	v_add_u32_e32 v3, 1, v5
	s_nop 0
	v_cndmask_b32_e32 v1, v1, v4, vcc
	v_mul_lo_u32 v4, v2, v1
	v_add_u32_e32 v2, v4, v2
	v_cmp_ne_u32_e32 vcc, v3, v2
	s_and_saveexec_b64 s[0:1], vcc
	s_xor_b64 s[8:9], exec, s[0:1]
	s_cbranch_execz .LBB0_1615
	s_waitcnt lgkmcnt(0)
	s_add_u32 s14, s70, 0xff20400
	s_addc_u32 s15, s71, 0
	v_mul_u32_u24_e32 v1, 2, v0
	v_mov_b32_e32 v0, 0
	global_load_dword v0, v0, s[14:15] sc1
	s_waitcnt vmcnt(0)
	v_cmp_lt_u32_e32 vcc, v0, v1
	s_and_saveexec_b64 s[10:11], vcc
	s_cbranch_execz .LBB0_1614
	s_add_u32 s12, s70, 0xff1d200
	s_addc_u32 s13, s71, 0
	s_mov_b32 s0, 1
	s_mov_b64 s[16:17], 0
	v_mov_b32_e32 v0, 0
	s_branch .LBB0_1605

; DI unsigned xb_ld(unsigned* p)              { return __hip_atomic_load(p, __ATOMIC_RELAXED, __HIP_MEMORY_SCOPE_AGENT); }
; #define XB_SPIN(cond, bar) do { unsigned _sp = 0; while (cond) { __builtin_amdgcn_s_sleep(1); \
;     if ((++_sp & 255u) == 0u) { if (xb_ld(&(bar)[XB_TMO])) break; if (_sp > XB_SPIN_CAP) { atomicAdd(&(bar)[XB_TMO], 1u); break; } } } } while (0)
; DI void xcd_barrier(const XcdBarrier& b) {
;     ...
;             XB_SPIN(xb_ld(&bar[XB_XGEN(b.x)]) == gen, bar);
.LBB0_1607:
	global_load_dword v2, v0, s[14:15] sc1
	s_add_i32 s0, s0, 1
	s_mov_b64 s[22:23], -1
	s_waitcnt vmcnt(0)
	v_cmp_ge_u32_e32 vcc, v2, v1
	s_orn2_b64 s[20:21], vcc, exec
	s_branch .LBB0_1604

; DI unsigned xb_ld(unsigned* p)              { return __hip_atomic_load(p, __ATOMIC_RELAXED, __HIP_MEMORY_SCOPE_AGENT); }
; DI unsigned xb_add(unsigned* p, unsigned v) { return __hip_atomic_fetch_add(p, v, __ATOMIC_RELAXED, __HIP_MEMORY_SCOPE_AGENT); }
; #define XB_SPIN(cond, bar) do { unsigned _sp = 0; while (cond) { __builtin_amdgcn_s_sleep(1); \
;     if ((++_sp & 255u) == 0u) { if (xb_ld(&(bar)[XB_TMO])) break; if (_sp > XB_SPIN_CAP) { atomicAdd(&(bar)[XB_TMO], 1u); break; } } } } while (0)
; DI void xcd_barrier(const XcdBarrier& b) {
;     ...
;             const unsigned og = xb_add(&bar[XB_TOP], 1u);
;             const unsigned tg = og / nx;
;             if (og + 1u == (tg + 1u) * nx) xb_add(&bar[XB_TOPGEN], 1u);
;             else XB_SPIN(xb_ld(&bar[XB_TOPGEN]) == tg, bar);
;             __builtin_amdgcn_fence(__ATOMIC_ACQUIRE, "agent");
.LBB0_1618:
	s_or_b64 exec, exec, s[10:11]
	v_cvt_f32_u32_e32 v3, v0
	s_waitcnt vmcnt(0)
	v_readfirstlane_b32 s0, v2
	s_add_u32 s10, s70, 0xff20400
	s_addc_u32 s11, s71, 0
	v_rcp_iflag_f32_e32 v3, v3
	v_add_u32_e32 v1, s0, v1
	v_add_u32_e32 v4, 1, v1
	s_mov_b64 s[12:13], 0
	v_mul_f32_e32 v2, 0x4f7ffffe, v3
	v_cvt_u32_f32_e32 v2, v2
	v_sub_u32_e32 v3, 0, v0
	v_mul_lo_u32 v3, v3, v2
	v_mul_hi_u32 v3, v2, v3
	v_add_u32_e32 v2, v2, v3
	v_mul_hi_u32 v2, v1, v2
	v_mul_lo_u32 v3, v2, v0
	v_sub_u32_e32 v1, v1, v3
	v_add_u32_e32 v5, 1, v2
	v_cmp_ge_u32_e32 vcc, v1, v0
	v_sub_u32_e32 v3, v1, v0
	s_nop 0
	v_cndmask_b32_e32 v2, v2, v5, vcc
	v_cndmask_b32_e32 v1, v1, v3, vcc
	v_add_u32_e32 v3, 1, v2
	v_cmp_ge_u32_e32 vcc, v1, v0
	s_nop 1
	v_cndmask_b32_e32 v2, v2, v3, vcc
	v_mul_lo_u32 v1, v0, v2
	v_add_u32_e32 v0, v1, v0
	v_cmp_ne_u32_e32 vcc, v4, v0
	v_mov_b32_e32 v5, v0
	v_mov_b64_e32 v[0:1], s[10:11]
	s_and_saveexec_b64 s[8:9], vcc
	s_cbranch_execz .LBB0_1630
	v_mov_b32_e32 v0, 0
	global_load_dword v1, v0, s[10:11] sc1
	s_mov_b64 s[16:17], 0
	s_waitcnt vmcnt(0)
	v_cmp_lt_u32_e32 vcc, v1, v5
	s_and_saveexec_b64 s[14:15], vcc
	s_cbranch_execz .LBB0_1629
	s_add_u32 s12, s70, 0xff1d200
	s_addc_u32 s13, s71, 0
	s_mov_b32 s0, 1
	s_branch .LBB0_1622

; DI unsigned xb_ld(unsigned* p)              { return __hip_atomic_load(p, __ATOMIC_RELAXED, __HIP_MEMORY_SCOPE_AGENT); }
; #define XB_SPIN(cond, bar) do { unsigned _sp = 0; while (cond) { __builtin_amdgcn_s_sleep(1); \
;     if ((++_sp & 255u) == 0u) { if (xb_ld(&(bar)[XB_TMO])) break; if (_sp > XB_SPIN_CAP) { atomicAdd(&(bar)[XB_TMO], 1u); break; } } } } while (0)
; DI void xcd_barrier(const XcdBarrier& b) {
;     ...
;             else XB_SPIN(xb_ld(&bar[XB_TOPGEN]) == tg, bar);
.LBB0_1624:
	global_load_dword v1, v0, s[10:11] sc1
	s_add_i32 s0, s0, 1
	s_mov_b64 s[20:21], -1
	s_waitcnt vmcnt(0)
	v_cmp_ge_u32_e32 vcc, v1, v5
	s_orn2_b64 s[24:25], vcc, exec
	s_branch .LBB0_1621

; DI unsigned xb_ld(unsigned* p)              { return __hip_atomic_load(p, __ATOMIC_RELAXED, __HIP_MEMORY_SCOPE_AGENT); }
; DI unsigned xb_add(unsigned* p, unsigned v) { return __hip_atomic_fetch_add(p, v, __ATOMIC_RELAXED, __HIP_MEMORY_SCOPE_AGENT); }
; #define XB_SPIN(cond, bar) do { unsigned _sp = 0; while (cond) { __builtin_amdgcn_s_sleep(1); \
;     if ((++_sp & 255u) == 0u) { if (xb_ld(&(bar)[XB_TMO])) break; if (_sp > XB_SPIN_CAP) { atomicAdd(&(bar)[XB_TMO], 1u); break; } } } } while (0)
; DI void xcd_barrier(const XcdBarrier& b) {
;     ...
;         const unsigned old = xb_add(&bar[XB_XSUB(b.x)], 1u);
;         const unsigned gen = old / nloc;
;         if (old + 1u == (gen + 1u) * nloc) {
;             __builtin_amdgcn_fence(__ATOMIC_RELEASE, "agent");
;             asm volatile("s_waitcnt vmcnt(0)" ::: "memory");
;             const unsigned og = xb_add(&bar[XB_TOP], 1u);
;             const unsigned tg = og / nx;
;             if (og + 1u == (tg + 1u) * nx) xb_add(&bar[XB_TOPGEN], 1u);
;             else XB_SPIN(xb_ld(&bar[XB_TOPGEN]) == tg, bar);
;             __builtin_amdgcn_fence(__ATOMIC_ACQUIRE, "agent");
;             xb_add(&bar[XB_XGEN(b.x)], 1u);
;             asm volatile("s_waitcnt vmcnt(0)" ::: "memory");
;         } else {
;             XB_SPIN(xb_ld(&bar[XB_XGEN(b.x)]) == gen, bar);
;             __builtin_amdgcn_fence(__ATOMIC_ACQUIRE, "agent");
;             asm volatile("s_waitcnt vmcnt(0)" ::: "memory");
;         }
.LBB0_1762:
	s_or_b64 exec, exec, s[10:11]
	v_cvt_f32_u32_e32 v4, v2
	s_waitcnt vmcnt(0)
	v_readfirstlane_b32 s0, v3
	v_sub_u32_e32 v3, 0, v2
	v_rcp_iflag_f32_e32 v4, v4
	v_add_u32_e32 v5, s0, v1
	v_mul_f32_e32 v4, 0x4f7ffffe, v4
	v_cvt_u32_f32_e32 v4, v4
	v_mul_lo_u32 v1, v3, v4
	v_mul_hi_u32 v1, v4, v1
	v_add_u32_e32 v1, v4, v1
	v_mul_hi_u32 v1, v5, v1
	v_mul_lo_u32 v3, v1, v2
	v_sub_u32_e32 v3, v5, v3
	v_add_u32_e32 v4, 1, v1
	v_cmp_ge_u32_e32 vcc, v3, v2
	s_nop 1
	v_cndmask_b32_e32 v1, v1, v4, vcc
	v_sub_u32_e32 v4, v3, v2
	v_cndmask_b32_e32 v3, v3, v4, vcc
	v_add_u32_e32 v4, 1, v1
	v_cmp_ge_u32_e32 vcc, v3, v2
	v_add_u32_e32 v3, 1, v5
	s_nop 0
	v_cndmask_b32_e32 v1, v1, v4, vcc
	v_mul_lo_u32 v4, v2, v1
	v_add_u32_e32 v2, v4, v2
	v_cmp_ne_u32_e32 vcc, v3, v2
	s_and_saveexec_b64 s[0:1], vcc
	s_xor_b64 s[8:9], exec, s[0:1]
	s_cbranch_execz .LBB0_1776
	s_waitcnt lgkmcnt(0)
	s_add_u32 s14, s70, 0xff20400
	s_addc_u32 s15, s71, 0
	v_mul_u32_u24_e32 v1, 3, v0
	v_mov_b32_e32 v0, 0
	global_load_dword v0, v0, s[14:15] sc1
	s_waitcnt vmcnt(0)
	v_cmp_lt_u32_e32 vcc, v0, v1
	s_and_saveexec_b64 s[10:11], vcc
	s_cbranch_execz .LBB0_1775
	s_add_u32 s12, s70, 0xff1d200
	s_addc_u32 s13, s71, 0
	s_mov_b32 s0, 1
	s_mov_b64 s[16:17], 0
	v_mov_b32_e32 v0, 0
	s_branch .LBB0_1766

; DI unsigned xb_ld(unsigned* p)              { return __hip_atomic_load(p, __ATOMIC_RELAXED, __HIP_MEMORY_SCOPE_AGENT); }
; DI unsigned xb_add(unsigned* p, unsigned v) { return __hip_atomic_fetch_add(p, v, __ATOMIC_RELAXED, __HIP_MEMORY_SCOPE_AGENT); }
; #define XB_SPIN(cond, bar) do { unsigned _sp = 0; while (cond) { __builtin_amdgcn_s_sleep(1); \
;     if ((++_sp & 255u) == 0u) { if (xb_ld(&(bar)[XB_TMO])) break; if (_sp > XB_SPIN_CAP) { atomicAdd(&(bar)[XB_TMO], 1u); break; } } } } while (0)
; DI void xcd_barrier(const XcdBarrier& b) {
;     ...
;         const unsigned old = xb_add(&bar[XB_XSUB(b.x)], 1u);
;         const unsigned gen = old / nloc;
;         if (old + 1u == (gen + 1u) * nloc) {
;             __builtin_amdgcn_fence(__ATOMIC_RELEASE, "agent");
;             asm volatile("s_waitcnt vmcnt(0)" ::: "memory");
;             const unsigned og = xb_add(&bar[XB_TOP], 1u);
;             const unsigned tg = og / nx;
;             if (og + 1u == (tg + 1u) * nx) xb_add(&bar[XB_TOPGEN], 1u);
;             else XB_SPIN(xb_ld(&bar[XB_TOPGEN]) == tg, bar);
;             __builtin_amdgcn_fence(__ATOMIC_ACQUIRE, "agent");
;             xb_add(&bar[XB_XGEN(b.x)], 1u);
;             asm volatile("s_waitcnt vmcnt(0)" ::: "memory");
;         } else {
;             XB_SPIN(xb_ld(&bar[XB_XGEN(b.x)]) == gen, bar);
;             __builtin_amdgcn_fence(__ATOMIC_ACQUIRE, "agent");
;             asm volatile("s_waitcnt vmcnt(0)" ::: "memory");
;         }
.LBB0_1873:
	s_or_b64 exec, exec, s[10:11]
	v_cvt_f32_u32_e32 v4, v2
	s_waitcnt vmcnt(0)
	v_readfirstlane_b32 s0, v3
	v_sub_u32_e32 v3, 0, v2
	v_rcp_iflag_f32_e32 v4, v4
	v_add_u32_e32 v5, s0, v1
	v_mul_f32_e32 v4, 0x4f7ffffe, v4
	v_cvt_u32_f32_e32 v4, v4
	v_mul_lo_u32 v1, v3, v4
	v_mul_hi_u32 v1, v4, v1
	v_add_u32_e32 v1, v4, v1
	v_mul_hi_u32 v1, v5, v1
	v_mul_lo_u32 v3, v1, v2
	v_sub_u32_e32 v3, v5, v3
	v_add_u32_e32 v4, 1, v1
	v_cmp_ge_u32_e32 vcc, v3, v2
	s_nop 1
	v_cndmask_b32_e32 v1, v1, v4, vcc
	v_sub_u32_e32 v4, v3, v2
	v_cndmask_b32_e32 v3, v3, v4, vcc
	v_add_u32_e32 v4, 1, v1
	v_cmp_ge_u32_e32 vcc, v3, v2
	v_add_u32_e32 v3, 1, v5
	s_nop 0
	v_cndmask_b32_e32 v1, v1, v4, vcc
	v_mul_lo_u32 v4, v2, v1
	v_add_u32_e32 v2, v4, v2
	v_cmp_ne_u32_e32 vcc, v3, v2
	s_and_saveexec_b64 s[8:9], vcc
	s_xor_b64 s[8:9], exec, s[8:9]
	s_cbranch_execz .LBB0_1887
	s_waitcnt lgkmcnt(0)
	s_add_u32 s14, s70, 0xff20400
	s_addc_u32 s15, s71, 0
	v_mul_u32_u24_e32 v1, 4, v0
	v_mov_b32_e32 v0, 0
	global_load_dword v0, v0, s[14:15] sc1
	s_waitcnt vmcnt(0)
	v_cmp_lt_u32_e32 vcc, v0, v1
	s_and_saveexec_b64 s[10:11], vcc
	s_cbranch_execz .LBB0_1886
	s_add_u32 s12, s70, 0xff1d200
	s_addc_u32 s13, s71, 0
	s_mov_b32 s0, 1
	s_mov_b64 s[16:17], 0
	v_mov_b32_e32 v0, 0
	s_branch .LBB0_1877

; DI unsigned xb_ld(unsigned* p)              { return __hip_atomic_load(p, __ATOMIC_RELAXED, __HIP_MEMORY_SCOPE_AGENT); }
; DI unsigned xb_add(unsigned* p, unsigned v) { return __hip_atomic_fetch_add(p, v, __ATOMIC_RELAXED, __HIP_MEMORY_SCOPE_AGENT); }
; #define XB_SPIN(cond, bar) do { unsigned _sp = 0; while (cond) { __builtin_amdgcn_s_sleep(1); \
;     if ((++_sp & 255u) == 0u) { if (xb_ld(&(bar)[XB_TMO])) break; if (_sp > XB_SPIN_CAP) { atomicAdd(&(bar)[XB_TMO], 1u); break; } } } } while (0)
; DI void xcd_barrier(const XcdBarrier& b) {
;     ...
;         const unsigned old = xb_add(&bar[XB_XSUB(b.x)], 1u);
;         const unsigned gen = old / nloc;
;         if (old + 1u == (gen + 1u) * nloc) {
;             __builtin_amdgcn_fence(__ATOMIC_RELEASE, "agent");
;             asm volatile("s_waitcnt vmcnt(0)" ::: "memory");
;             const unsigned og = xb_add(&bar[XB_TOP], 1u);
;             const unsigned tg = og / nx;
;             if (og + 1u == (tg + 1u) * nx) xb_add(&bar[XB_TOPGEN], 1u);
;             else XB_SPIN(xb_ld(&bar[XB_TOPGEN]) == tg, bar);
;             __builtin_amdgcn_fence(__ATOMIC_ACQUIRE, "agent");
;             xb_add(&bar[XB_XGEN(b.x)], 1u);
;             asm volatile("s_waitcnt vmcnt(0)" ::: "memory");
;         } else {
;             XB_SPIN(xb_ld(&bar[XB_XGEN(b.x)]) == gen, bar);
;             __builtin_amdgcn_fence(__ATOMIC_ACQUIRE, "agent");
;             asm volatile("s_waitcnt vmcnt(0)" ::: "memory");
;         }
.LBB0_1957:
	s_or_b64 exec, exec, s[16:17]
	v_cvt_f32_u32_e32 v4, v2
	s_waitcnt vmcnt(0)
	v_readfirstlane_b32 s0, v3
	v_sub_u32_e32 v3, 0, v2
	v_rcp_iflag_f32_e32 v4, v4
	v_add_u32_e32 v5, s0, v1
	v_mul_f32_e32 v4, 0x4f7ffffe, v4
	v_cvt_u32_f32_e32 v4, v4
	v_mul_lo_u32 v1, v3, v4
	v_mul_hi_u32 v1, v4, v1
	v_add_u32_e32 v1, v4, v1
	v_mul_hi_u32 v1, v5, v1
	v_mul_lo_u32 v3, v1, v2
	v_sub_u32_e32 v3, v5, v3
	v_add_u32_e32 v4, 1, v1
	v_cmp_ge_u32_e32 vcc, v3, v2
	s_nop 1
	v_cndmask_b32_e32 v1, v1, v4, vcc
	v_sub_u32_e32 v4, v3, v2
	v_cndmask_b32_e32 v3, v3, v4, vcc
	v_add_u32_e32 v4, 1, v1
	v_cmp_ge_u32_e32 vcc, v3, v2
	v_add_u32_e32 v3, 1, v5
	s_nop 0
	v_cndmask_b32_e32 v1, v1, v4, vcc
	v_mul_lo_u32 v4, v2, v1
	v_add_u32_e32 v2, v4, v2
	v_cmp_ne_u32_e32 vcc, v3, v2
	s_and_saveexec_b64 s[0:1], vcc
	s_xor_b64 s[14:15], exec, s[0:1]
	s_cbranch_execz .LBB0_1971
	s_waitcnt lgkmcnt(0)
	s_add_u32 s20, s70, 0xff20400
	s_addc_u32 s21, s71, 0
	v_mul_u32_u24_e32 v1, 5, v0
	v_mov_b32_e32 v0, 0
	global_load_dword v0, v0, s[20:21] sc1
	s_waitcnt vmcnt(0)
	v_cmp_lt_u32_e32 vcc, v0, v1
	s_and_saveexec_b64 s[16:17], vcc
	s_cbranch_execz .LBB0_1970
	s_add_u32 s18, s70, 0xff1d200
	s_addc_u32 s19, s71, 0
	s_mov_b32 s0, 1
	s_mov_b64 s[22:23], 0
	v_mov_b32_e32 v0, 0
	s_branch .LBB0_1961

; DI unsigned xb_ld(unsigned* p)              { return __hip_atomic_load(p, __ATOMIC_RELAXED, __HIP_MEMORY_SCOPE_AGENT); }
; #define XB_SPIN(cond, bar) do { unsigned _sp = 0; while (cond) { __builtin_amdgcn_s_sleep(1); \
;     if ((++_sp & 255u) == 0u) { if (xb_ld(&(bar)[XB_TMO])) break; if (_sp > XB_SPIN_CAP) { atomicAdd(&(bar)[XB_TMO], 1u); break; } } } } while (0)
; DI void xcd_barrier(const XcdBarrier& b) {
;     ...
;             XB_SPIN(xb_ld(&bar[XB_XGEN(b.x)]) == gen, bar);
.LBB0_1963:
	global_load_dword v2, v0, s[20:21] sc1
	s_add_i32 s0, s0, 1
	s_mov_b64 s[28:29], -1
	s_waitcnt vmcnt(0)
	v_cmp_ge_u32_e32 vcc, v2, v1
	s_orn2_b64 s[26:27], vcc, exec
	s_branch .LBB0_1960

; DI unsigned xb_ld(unsigned* p)              { return __hip_atomic_load(p, __ATOMIC_RELAXED, __HIP_MEMORY_SCOPE_AGENT); }
; DI unsigned xb_add(unsigned* p, unsigned v) { return __hip_atomic_fetch_add(p, v, __ATOMIC_RELAXED, __HIP_MEMORY_SCOPE_AGENT); }
; #define XB_SPIN(cond, bar) do { unsigned _sp = 0; while (cond) { __builtin_amdgcn_s_sleep(1); \
;     if ((++_sp & 255u) == 0u) { if (xb_ld(&(bar)[XB_TMO])) break; if (_sp > XB_SPIN_CAP) { atomicAdd(&(bar)[XB_TMO], 1u); break; } } } } while (0)
; DI void xcd_barrier(const XcdBarrier& b) {
;     ...
;             const unsigned og = xb_add(&bar[XB_TOP], 1u);
;             const unsigned tg = og / nx;
;             if (og + 1u == (tg + 1u) * nx) xb_add(&bar[XB_TOPGEN], 1u);
;             else XB_SPIN(xb_ld(&bar[XB_TOPGEN]) == tg, bar);
;             __builtin_amdgcn_fence(__ATOMIC_ACQUIRE, "agent");
.LBB0_1974:
	s_or_b64 exec, exec, s[16:17]
	v_cvt_f32_u32_e32 v3, v0
	s_waitcnt vmcnt(0)
	v_readfirstlane_b32 s0, v2
	s_add_u32 s16, s70, 0xff20400
	s_addc_u32 s17, s71, 0
	v_rcp_iflag_f32_e32 v3, v3
	v_add_u32_e32 v1, s0, v1
	v_add_u32_e32 v4, 1, v1
	s_mov_b64 s[18:19], 0
	v_mul_f32_e32 v2, 0x4f7ffffe, v3
	v_cvt_u32_f32_e32 v2, v2
	v_sub_u32_e32 v3, 0, v0
	v_mul_lo_u32 v3, v3, v2
	v_mul_hi_u32 v3, v2, v3
	v_add_u32_e32 v2, v2, v3
	v_mul_hi_u32 v2, v1, v2
	v_mul_lo_u32 v3, v2, v0
	v_sub_u32_e32 v1, v1, v3
	v_add_u32_e32 v5, 1, v2
	v_cmp_ge_u32_e32 vcc, v1, v0
	v_sub_u32_e32 v3, v1, v0
	s_nop 0
	v_cndmask_b32_e32 v2, v2, v5, vcc
	v_cndmask_b32_e32 v1, v1, v3, vcc
	v_add_u32_e32 v3, 1, v2
	v_cmp_ge_u32_e32 vcc, v1, v0
	s_nop 1
	v_cndmask_b32_e32 v2, v2, v3, vcc
	v_mul_lo_u32 v1, v0, v2
	v_add_u32_e32 v0, v1, v0
	v_cmp_ne_u32_e32 vcc, v4, v0
	v_mov_b32_e32 v5, v0
	v_mov_b64_e32 v[0:1], s[16:17]
	s_and_saveexec_b64 s[14:15], vcc
	s_cbranch_execz .LBB0_1986
	v_mov_b32_e32 v0, 0
	global_load_dword v1, v0, s[16:17] sc1
	s_mov_b64 s[22:23], 0
	s_waitcnt vmcnt(0)
	v_cmp_lt_u32_e32 vcc, v1, v5
	s_and_saveexec_b64 s[20:21], vcc
	s_cbranch_execz .LBB0_1985
	s_add_u32 s18, s70, 0xff1d200
	s_addc_u32 s19, s71, 0
	s_mov_b32 s0, 1
	s_branch .LBB0_1978

; DI unsigned xb_ld(unsigned* p)              { return __hip_atomic_load(p, __ATOMIC_RELAXED, __HIP_MEMORY_SCOPE_AGENT); }
; #define XB_SPIN(cond, bar) do { unsigned _sp = 0; while (cond) { __builtin_amdgcn_s_sleep(1); \
;     if ((++_sp & 255u) == 0u) { if (xb_ld(&(bar)[XB_TMO])) break; if (_sp > XB_SPIN_CAP) { atomicAdd(&(bar)[XB_TMO], 1u); break; } } } } while (0)
; DI void xcd_barrier(const XcdBarrier& b) {
;     ...
;             else XB_SPIN(xb_ld(&bar[XB_TOPGEN]) == tg, bar);
.LBB0_1980:
	global_load_dword v1, v0, s[16:17] sc1
	s_add_i32 s0, s0, 1
	s_mov_b64 s[26:27], -1
	s_waitcnt vmcnt(0)
	v_cmp_ge_u32_e32 vcc, v1, v5
	s_orn2_b64 s[30:31], vcc, exec
	s_branch .LBB0_1977
